# attnA combine loop: two items per trip, both items' loads in flight before the wait
# baseline (speedup 1.0000x reference)
; __device__ __forceinline__ void attnA_combine(const unsigned char* ws, int vcu, int G) {
;     const bf16* A0 = (const bf16*)(ws + WS_AO0); const bf16* A1 = (const bf16*)(ws + WS_AO1); const bf16* A2 = (const bf16*)(ws + WS_AO2);
;     const float* LSE = (const float*)(ws + WS_LSE); bf16* O = (bf16*)(ws + WS_ATTA);
;     for (size_t it = (size_t)vcu * 512 + threadIdx.x; it < (size_t)M * 64; it += (size_t)G * 512) {
;         const size_t rh = it >> 3;
;         const float l0 = LSE[rh], l1 = LSE[(size_t)M * 8 + rh], l2 = LSE[(size_t)2 * M * 8 + rh];
;         const float mx = fmaxf(l0, fmaxf(l1, l2));
;         float w0 = __builtin_amdgcn_exp2f(l0 - mx), w1 = __builtin_amdgcn_exp2f(l1 - mx), w2 = __builtin_amdgcn_exp2f(l2 - mx);
;         const float inv = 1.0f / (w0 + w1 + w2); w0 *= inv; w1 *= inv; w2 *= inv;
;         const u32x4 a = *(const u32x4*)(A0 + it * 8), bq = *(const u32x4*)(A1 + it * 8), c = *(const u32x4*)(A2 + it * 8);
.LBB0_283:
	v_readlane_b32 s4, v254, 2
	v_readlane_b32 s5, v254, 3
	s_cmp_lt_i32 s4, 4
	s_cselect_b64 s[4:5], -1, 0
	s_and_b64 s[20:21], s[4:5], s[0:1]
	s_andn2_b64 vcc, exec, s[20:21]
	s_cbranch_vccnz .LBB0_311
	s_ashr_i32 s79, s78, 31
	v_mov_b32_e32 v1, 0
	s_lshl_b64 s[0:1], s[78:79], 9
	v_mov_b32_e32 v161, v1
	v_lshl_add_u64 v[2:3], s[0:1], 0, v[160:161]
	s_mov_b64 s[0:1], 0x400000
	v_cmp_gt_u64_e32 vcc, s[0:1], v[2:3]
	s_and_saveexec_b64 s[0:1], vcc
	s_cbranch_execz .LBB0_287
	s_add_u32 s4, s76, 0x3de00000
	s_addc_u32 s5, s77, 0
	s_add_u32 s6, s76, 0x34000000
	s_addc_u32 s7, s77, 0
	s_lshl_b64 s[10:11], s[78:79], 13
	v_lshlrev_b32_e32 v0, 4, v160
	s_ashr_i32 s43, s42, 31
	v_lshl_add_u64 v[4:5], s[10:11], 0, v[0:1]
	s_lshl_b64 s[12:13], s[78:79], 12
	v_lshlrev_b32_e32 v0, 3, v160
	s_lshl_b64 s[8:9], s[42:43], 9
	s_lshl_b64 s[10:11], s[42:43], 13
	v_lshl_add_u64 v[6:7], s[12:13], 0, v[0:1]
	s_lshl_b64 s[12:13], s[42:43], 12
	s_mov_b64 s[14:15], 0
	s_brev_b32 s3, 32
	s_brev_b32 s18, 12
	s_mov_b64 s[16:17], 0x3fffff
	v_mov_b32_e32 v43, 0
.LBB0_286:
	v_lshl_add_u64 v[12:13], s[76:77], 0, v[4:5]
	v_add_co_u32_e32 v10, vcc, s3, v12
	v_lshrrev_b64 v[8:9], 1, v[2:3]
	s_nop 0
	v_addc_co_u32_e32 v11, vcc, 0, v13, vcc
	v_and_b32_e32 v8, -4, v8
	v_add_co_u32_e32 v16, vcc, s18, v12
	v_lshl_add_u64 v[14:15], s[4:5], 0, v[8:9]
	s_nop 0
	v_addc_co_u32_e32 v17, vcc, 0, v13, vcc
	v_add_co_u32_e32 v18, vcc, 0x200000, v14
	global_load_dwordx4 v[8:11], v[10:11], off
	s_nop 0
	global_load_dword v38, v[14:15], off
	v_addc_co_u32_e32 v19, vcc, 0, v15, vcc
	v_add_co_u32_e32 v14, vcc, 0x400000, v14
	v_and_b32_e32 v0, 0x3fffc00, v4
	s_nop 0
	v_addc_co_u32_e32 v15, vcc, 0, v15, vcc
	global_load_dword v39, v[18:19], off
	global_load_dword v40, v[14:15], off
	s_nop 0
	global_load_dwordx4 v[12:15], v[12:13], off
	s_nop 0
	global_load_dwordx4 v[16:19], v[16:17], off
	v_and_b32_e32 v22, 0x1f8, v6
	v_lshlrev_b32_e32 v0, 1, v0
	v_lshl_add_u64 v[20:21], s[6:7], 0, v[0:1]
	v_lshlrev_b32_e32 v0, 1, v22
	v_lshl_add_u64 v[20:21], v[20:21], 0, v[0:1]
	v_lshl_add_u64 v[2:3], v[2:3], 0, s[8:9]
	v_cmp_lt_u64_e32 vcc, s[16:17], v[2:3]
	s_or_b64 s[14:15], vcc, s[14:15]
	v_lshl_add_u64 v[4:5], v[4:5], 0, s[10:11]
	v_lshl_add_u64 v[6:7], v[6:7], 0, s[12:13]
	s_mov_b64 s[24:25], exec
	s_andn2_b64 exec, exec, s[14:15]
	v_lshl_add_u64 v[52:53], s[76:77], 0, v[4:5]
	v_add_co_u32_e32 v50, vcc, s3, v52
	v_lshrrev_b64 v[48:49], 1, v[2:3]
	s_nop 0
	v_addc_co_u32_e32 v51, vcc, 0, v53, vcc
	v_and_b32_e32 v48, -4, v48
	v_add_co_u32_e32 v56, vcc, s18, v52
	v_lshl_add_u64 v[54:55], s[4:5], 0, v[48:49]
	s_nop 0
	v_addc_co_u32_e32 v57, vcc, 0, v53, vcc
	v_add_co_u32_e32 v58, vcc, 0x200000, v54
	global_load_dwordx4 v[48:51], v[50:51], off
	s_nop 0
	global_load_dword v78, v[54:55], off
	v_addc_co_u32_e32 v59, vcc, 0, v55, vcc
	v_add_co_u32_e32 v54, vcc, 0x400000, v54
	v_and_b32_e32 v42, 0x3fffc00, v4
	s_nop 0
	v_addc_co_u32_e32 v55, vcc, 0, v55, vcc
	global_load_dword v79, v[58:59], off
	global_load_dword v80, v[54:55], off
	s_nop 0
	global_load_dwordx4 v[52:55], v[52:53], off
	s_nop 0
	global_load_dwordx4 v[56:59], v[56:57], off
	v_and_b32_e32 v62, 0x1f8, v6
	v_lshlrev_b32_e32 v42, 1, v42
	v_lshl_add_u64 v[60:61], s[6:7], 0, v[42:43]
	v_lshlrev_b32_e32 v42, 1, v62
	v_lshl_add_u64 v[60:61], v[60:61], 0, v[42:43]
	v_lshl_add_u64 v[2:3], v[2:3], 0, s[8:9]
	v_cmp_lt_u64_e32 vcc, s[16:17], v[2:3]
	s_or_b64 s[14:15], vcc, s[14:15]
	v_lshl_add_u64 v[4:5], v[4:5], 0, s[10:11]
	v_lshl_add_u64 v[6:7], v[6:7], 0, s[12:13]
	s_waitcnt vmcnt(0)
; __device__ __forceinline__ unsigned pk2(float lo, float hi) { f32x2 v = {lo, hi}; bf16x2_t b = __builtin_convertvector(v, bf16x2_t); return __builtin_bit_cast(unsigned, b); }
; __device__ __forceinline__ float bflo(unsigned w) { return __uint_as_float(w << 16); }
; __device__ __forceinline__ float bfhi(unsigned w) { return __uint_as_float(w & 0xffff0000u); }
; __device__ __forceinline__ void attnA_combine(const unsigned char* ws, int vcu, int G) {
;     ...
;     for (size_t it = (size_t)vcu * 512 + threadIdx.x; it < (size_t)M * 64; it += (size_t)G * 512) {
;         const size_t rh = it >> 3;
;         const float l0 = LSE[rh], l1 = LSE[(size_t)M * 8 + rh], l2 = LSE[(size_t)2 * M * 8 + rh];
;         const float mx = fmaxf(l0, fmaxf(l1, l2));
;         float w0 = __builtin_amdgcn_exp2f(l0 - mx), w1 = __builtin_amdgcn_exp2f(l1 - mx), w2 = __builtin_amdgcn_exp2f(l2 - mx);
;         const float inv = 1.0f / (w0 + w1 + w2); w0 *= inv; w1 *= inv; w2 *= inv;
;         const u32x4 a = *(const u32x4*)(A0 + it * 8), bq = *(const u32x4*)(A1 + it * 8), c = *(const u32x4*)(A2 + it * 8);
;         u32x4 o;
; #pragma unroll
;         for (int k = 0; k < 4; ++k) o[k] = pk2(w0 * bflo(a[k]) + w1 * bflo(bq[k]) + w2 * bflo(c[k]), w0 * bfhi(a[k]) + w1 * bfhi(bq[k]) + w2 * bfhi(c[k]));
;         *(u32x4*)(O + (it >> 6) * 1024 + (it & 63) * 8) = o;
;     }
	v_lshlrev_b32_e32 v62, 16, v48
	v_and_b32_e32 v65, 0xffff0000, v48
	v_lshlrev_b32_e32 v48, 16, v49
	v_and_b32_e32 v69, 0xffff0000, v49
	v_lshlrev_b32_e32 v70, 16, v50
	v_and_b32_e32 v73, 0xffff0000, v50
	v_lshlrev_b32_e32 v50, 16, v51
	v_max3_f32 v42, v78, v79, v80
	v_and_b32_e32 v63, 0xffff0000, v52
	v_lshlrev_b32_e32 v64, 16, v52
	v_and_b32_e32 v71, 0xffff0000, v54
	v_lshlrev_b32_e32 v72, 16, v54
	v_sub_f32_e32 v52, v78, v42
	v_sub_f32_e32 v54, v79, v42
	v_and_b32_e32 v49, 0xffff0000, v53
	v_lshlrev_b32_e32 v68, 16, v53
	v_sub_f32_e32 v42, v80, v42
	v_exp_f32_e32 v53, v52
	v_exp_f32_e32 v52, v54
	v_exp_f32_e32 v54, v42
	v_and_b32_e32 v77, 0xffff0000, v51
	v_and_b32_e32 v51, 0xffff0000, v55
	v_add_f32_e32 v42, v53, v52
	v_add_f32_e32 v42, v54, v42
	v_lshlrev_b32_e32 v76, 16, v55
	v_div_scale_f32 v55, s[22:23], v42, v42, 1.0
	v_rcp_f32_e32 v79, v55
	v_div_scale_f32 v78, vcc, 1.0, v42, 1.0
	v_lshlrev_b32_e32 v66, 16, v56
	v_fma_f32 v80, -v55, v79, 1.0
	v_fmac_f32_e32 v79, v80, v79
	v_mul_f32_e32 v80, v78, v79
	v_fma_f32 v81, -v55, v80, v78
	v_fmac_f32_e32 v80, v81, v79
	v_fma_f32 v55, -v55, v80, v78
	v_div_fmas_f32 v55, v55, v79, v80
	v_div_fixup_f32 v42, v55, v42, 1.0
	v_pk_mul_f32 v[52:53], v[52:53], v[42:43] op_sel_hi:[1,0]
	v_and_b32_e32 v67, 0xffff0000, v56
	v_pk_mul_f32 v[64:65], v[52:53], v[64:65] op_sel:[1,0] op_sel_hi:[0,1]
	v_pk_mul_f32 v[68:69], v[52:53], v[68:69] op_sel:[1,0] op_sel_hi:[0,1]
	v_pk_mul_f32 v[72:73], v[52:53], v[72:73] op_sel:[1,0] op_sel_hi:[0,1]
	v_pk_mul_f32 v[76:77], v[52:53], v[76:77] op_sel:[1,0] op_sel_hi:[0,1]
	v_lshlrev_b32_e32 v56, 16, v57
	v_and_b32_e32 v57, 0xffff0000, v57
	v_lshlrev_b32_e32 v74, 16, v58
	v_and_b32_e32 v75, 0xffff0000, v58
	v_lshlrev_b32_e32 v58, 16, v59
	v_and_b32_e32 v59, 0xffff0000, v59
	v_mul_f32_e32 v54, v54, v42
	v_pk_fma_f32 v[62:63], v[52:53], v[62:63], v[64:65]
	v_pk_fma_f32 v[48:49], v[52:53], v[48:49], v[68:69]
	v_pk_fma_f32 v[64:65], v[52:53], v[70:71], v[72:73]
	v_pk_fma_f32 v[50:51], v[52:53], v[50:51], v[76:77]
	v_pk_fma_f32 v[52:53], v[54:55], v[66:67], v[62:63] op_sel_hi:[0,1,1]
	v_pk_fma_f32 v[56:57], v[54:55], v[56:57], v[48:49] op_sel_hi:[0,1,1]
	v_pk_fma_f32 v[62:63], v[54:55], v[74:75], v[64:65] op_sel_hi:[0,1,1]
	v_pk_fma_f32 v[54:55], v[54:55], v[58:59], v[50:51] op_sel_hi:[0,1,1]
	v_cvt_pk_bf16_f32 v48, v52, v53
	v_cvt_pk_bf16_f32 v49, v56, v57
	v_cvt_pk_bf16_f32 v50, v62, v63
	v_cvt_pk_bf16_f32 v51, v54, v55
	global_store_dwordx4 v[60:61], v[48:51], off
	s_mov_b64 exec, s[24:25]
	v_lshlrev_b32_e32 v22, 16, v8
	v_and_b32_e32 v25, 0xffff0000, v8
	v_lshlrev_b32_e32 v8, 16, v9
	v_and_b32_e32 v29, 0xffff0000, v9
	v_lshlrev_b32_e32 v30, 16, v10
	v_and_b32_e32 v33, 0xffff0000, v10
	v_lshlrev_b32_e32 v10, 16, v11
	v_max3_f32 v0, v38, v39, v40
	v_and_b32_e32 v23, 0xffff0000, v12
	v_lshlrev_b32_e32 v24, 16, v12
	v_and_b32_e32 v31, 0xffff0000, v14
	v_lshlrev_b32_e32 v32, 16, v14
	v_sub_f32_e32 v12, v38, v0
	v_sub_f32_e32 v14, v39, v0
	v_and_b32_e32 v9, 0xffff0000, v13
	v_lshlrev_b32_e32 v28, 16, v13
	v_sub_f32_e32 v0, v40, v0
	v_exp_f32_e32 v13, v12
	v_exp_f32_e32 v12, v14
	v_exp_f32_e32 v14, v0
	v_and_b32_e32 v37, 0xffff0000, v11
	v_and_b32_e32 v11, 0xffff0000, v15
	v_add_f32_e32 v0, v13, v12
	v_add_f32_e32 v0, v14, v0
	v_lshlrev_b32_e32 v36, 16, v15
	v_div_scale_f32 v15, s[22:23], v0, v0, 1.0
	v_rcp_f32_e32 v39, v15
	v_div_scale_f32 v38, vcc, 1.0, v0, 1.0
	v_lshlrev_b32_e32 v26, 16, v16
	v_fma_f32 v40, -v15, v39, 1.0
	v_fmac_f32_e32 v39, v40, v39
	v_mul_f32_e32 v40, v38, v39
	v_fma_f32 v41, -v15, v40, v38
	v_fmac_f32_e32 v40, v41, v39
	v_fma_f32 v15, -v15, v40, v38
	v_div_fmas_f32 v15, v15, v39, v40
	v_div_fixup_f32 v0, v15, v0, 1.0
	v_pk_mul_f32 v[12:13], v[12:13], v[0:1] op_sel_hi:[1,0]
	v_and_b32_e32 v27, 0xffff0000, v16
	v_pk_mul_f32 v[24:25], v[12:13], v[24:25] op_sel:[1,0] op_sel_hi:[0,1]
	v_pk_mul_f32 v[28:29], v[12:13], v[28:29] op_sel:[1,0] op_sel_hi:[0,1]
	v_pk_mul_f32 v[32:33], v[12:13], v[32:33] op_sel:[1,0] op_sel_hi:[0,1]
	v_pk_mul_f32 v[36:37], v[12:13], v[36:37] op_sel:[1,0] op_sel_hi:[0,1]
	v_lshlrev_b32_e32 v16, 16, v17
	v_and_b32_e32 v17, 0xffff0000, v17
	v_lshlrev_b32_e32 v34, 16, v18
	v_and_b32_e32 v35, 0xffff0000, v18
	v_lshlrev_b32_e32 v18, 16, v19
	v_and_b32_e32 v19, 0xffff0000, v19
	v_mul_f32_e32 v14, v14, v0
	v_pk_fma_f32 v[22:23], v[12:13], v[22:23], v[24:25]
	v_pk_fma_f32 v[8:9], v[12:13], v[8:9], v[28:29]
	v_pk_fma_f32 v[24:25], v[12:13], v[30:31], v[32:33]
	v_pk_fma_f32 v[10:11], v[12:13], v[10:11], v[36:37]
	v_pk_fma_f32 v[12:13], v[14:15], v[26:27], v[22:23] op_sel_hi:[0,1,1]
	v_pk_fma_f32 v[16:17], v[14:15], v[16:17], v[8:9] op_sel_hi:[0,1,1]
	v_pk_fma_f32 v[22:23], v[14:15], v[34:35], v[24:25] op_sel_hi:[0,1,1]
	v_pk_fma_f32 v[14:15], v[14:15], v[18:19], v[10:11] op_sel_hi:[0,1,1]
	v_cvt_pk_bf16_f32 v8, v12, v13
	v_cvt_pk_bf16_f32 v9, v16, v17
	v_cvt_pk_bf16_f32 v10, v22, v23
	v_cvt_pk_bf16_f32 v11, v14, v15
	global_store_dwordx4 v[20:21], v[8:11], off
	s_andn2_b64 exec, exec, s[14:15]
	s_cbranch_execnz .LBB0_286
